# attention softmax: row sums via pairwise packed-add tree (8 ops instead of 15 dependent adds per query block)
# baseline (speedup 1.0000x reference)
; __device__ __forceinline__ void attn_unit(const Params& p, int b, int h, int q0, int nkeys, unsigned char* lds, int do_write) {
;     ...
; #pragma unroll
;                 for (int km = 0; km < 4; ++km)
; #pragma unroll
;                     for (int j = 0; j < 4; ++j) { const float e = __builtin_amdgcn_exp2f(sacc[km][nq][j]); sacc[km][nq][j] = e; ps += e; }
;             }
;             psum[nq] = ps;
.LBB0_588:
	s_andn2_b64 vcc, exec, s[80:81]
	s_cbranch_vccnz .LBB0_590
	v_exp_f32_e32 v116, v72
	v_exp_f32_e32 v117, v73
	v_exp_f32_e32 v118, v74
	v_exp_f32_e32 v119, v75
	v_exp_f32_e32 v120, v76
	v_exp_f32_e32 v121, v77
	v_exp_f32_e32 v122, v78
	v_exp_f32_e32 v123, v79
	v_exp_f32_e32 v124, v80
	v_exp_f32_e32 v125, v81
	v_exp_f32_e32 v126, v82
	v_exp_f32_e32 v127, v83
	v_exp_f32_e32 v128, v84
	v_exp_f32_e32 v129, v85
	v_exp_f32_e32 v130, v86
	v_mov_b32_e32 v131, v87
	v_pk_add_f32 v[166:167], v[116:117], v[118:119]
	v_pk_add_f32 v[168:169], v[120:121], v[122:123]
	v_pk_add_f32 v[170:171], v[124:125], v[126:127]
	v_pk_add_f32 v[166:167], v[166:167], v[168:169]
	v_pk_add_f32 v[170:171], v[170:171], v[128:129]
	v_pk_add_f32 v[166:167], v[166:167], v[170:171]
	v_add_f32_e32 v72, v166, v167
	v_add_f32_e32 v115, v130, v72

; __device__ __forceinline__ void attn_unit(const Params& p, int b, int h, int q0, int nkeys, unsigned char* lds, int do_write) {
;     ...
; #pragma unroll
;                 for (int km = 0; km < 4; ++km)
; #pragma unroll
;                     for (int j = 0; j < 4; ++j) { const float e = __builtin_amdgcn_exp2f(sacc[km][nq][j]); sacc[km][nq][j] = e; ps += e; }
;             }
;             psum[nq] = ps;
.LBB0_592:
	s_andn2_b64 vcc, exec, s[80:81]
	s_cbranch_vccnz .LBB0_594
	v_exp_f32_e32 v81, v56
	v_exp_f32_e32 v82, v57
	v_exp_f32_e32 v83, v58
	v_exp_f32_e32 v84, v59
	v_exp_f32_e32 v85, v60
	v_exp_f32_e32 v86, v61
	v_exp_f32_e32 v87, v62
	v_exp_f32_e32 v116, v63
	v_exp_f32_e32 v117, v64
	v_exp_f32_e32 v118, v65
	v_exp_f32_e32 v119, v66
	v_exp_f32_e32 v120, v67
	v_exp_f32_e32 v121, v68
	v_exp_f32_e32 v122, v69
	v_exp_f32_e32 v123, v70
	v_mov_b32_e32 v125, v71
	v_pk_add_f32 v[166:167], v[82:83], v[84:85]
	v_pk_add_f32 v[168:169], v[86:87], v[116:117]
	v_pk_add_f32 v[170:171], v[118:119], v[120:121]
	v_pk_add_f32 v[166:167], v[166:167], v[168:169]
	v_pk_add_f32 v[170:171], v[170:171], v[122:123]
	v_pk_add_f32 v[166:167], v[166:167], v[170:171]
	v_add_f32_e32 v56, v166, v167
	v_add_f32_e32 v124, v81, v56
